# on top of v25: attention work units permuted across workgroups so that all 32 units of one (batch, head, dilation pattern) run on workgroups of one XCD, turning the 1.5x K/V halo re-reads into L2 hits
# baseline (speedup 1.0000x reference)
; __device__ __forceinline__ void attn_mfma(const GAS bf16* proj, GAS bf16* part, GAS float* lse, int TOKG, const GAS float* qgain, const GAS float* kgain, const GAS float* rel_bias,
;                                           unsigned char* lds, int tid, int lane, int wave, int bid, int G) {
;     ...
;     if (bid < nunits) ATT_ISSUE(bid);
;     for (int u = bid; u < nunits; u += G) {
.LBB0_4:
	s_or_b64 exec, exec, s[0:1]
	s_lshl_b32 s0, s2, 3
	v_lshrrev_b32_e32 v1, 20, v0
	v_lshrrev_b32_e32 v0, 10, v0
	s_mul_i32 s58, s51, s50
	v_writelane_b32 v236, s0, 2
	v_or_b32_e32 v0, v0, v1
	s_movk_i32 s0, 0x3ff
	s_ashr_i32 s51, s2, 31
	v_and_or_b32 v0, v0, s0, v186
	s_lshr_b32 s0, s51, 29
	s_add_i32 s0, s2, s0
	s_ashr_i32 s1, s0, 3
	s_and_b32 s0, s0, -8
	s_lshl_b32 s33, s50, 3
	s_lshl_b32 s52, s50, 4
	s_sub_i32 s75, s2, s0
	s_cmp_gt_i32 s75, -1
	v_writelane_b32 v236, s1, 3
	s_cselect_b64 s[0:1], -1, 0
	v_writelane_b32 v236, s0, 4
	s_mul_i32 s58, s58, s3
	s_add_i32 s78, 0, 0x26080
	v_writelane_b32 v236, s1, 5
	s_lshr_b32 s4, s50, 3
	s_and_b32 s101, s2, 7
	s_mul_i32 s101, s101, s4
	s_lshr_b32 s4, s2, 3
	s_add_i32 s101, s101, s4
	s_ashr_i32 s0, s101, 5
	s_mul_hi_i32 s3, s0, 0x55555556
	s_lshr_b32 s4, s3, 31
	s_add_i32 s3, s3, s4
	s_mul_i32 s4, s3, 3
	s_sub_i32 s4, s0, s4
	s_lshl_b32 s5, s4, 1
	s_and_b32 s1, s101, 31
	s_lshl_b32 s4, -1, s5
	s_ashr_i32 s0, s3, 4
	s_andn2_b32 s4, s1, s4
	s_lshr_b32 s1, s1, s5
	v_writelane_b32 v236, s5, 6
	s_lshl_b32 s5, s1, 8
	s_ashr_i32 s1, s0, 31
	s_lshl_b64 s[0:1], s[0:1], 13
	v_writelane_b32 v236, s5, 7
	s_addk_i32 s5, 0xff80
	v_writelane_b32 v236, s5, 8
	s_or_b32 s0, s0, s4
	v_writelane_b32 v236, s0, 9
	s_add_i32 s79, 0, 0x26078
	s_add_i32 s80, 0, 0x26070
	v_writelane_b32 v236, s1, 10
	s_lshr_b32 s1, s75, 31
	v_writelane_b32 v236, s1, 11
	s_lshl_b32 s1, s2, 4
	s_lshl_b32 s0, s3, 6
	s_or_b32 s3, s1, 2
	v_writelane_b32 v236, s3, 12
	s_lshl_b32 s3, s2, 19
	s_or_b32 s4, s3, 0x10000
	v_writelane_b32 v236, s4, 13
	s_lshl_b32 s4, s2, 23
	s_or_b32 s5, s4, 0x100000
	v_writelane_b32 v236, s5, 14
	s_or_b32 s1, s1, 1
	v_writelane_b32 v236, s1, 15
	s_or_b32 s1, s3, 0x8000
	v_writelane_b32 v236, s1, 16
	s_or_b32 s1, s4, 0x80000
	v_writelane_b32 v236, s1, 17
	s_lshl_b32 s1, s2, 10
	v_writelane_b32 v236, s1, 18
	s_lshl_b32 s1, s50, 10
	v_writelane_b32 v236, s1, 19
	s_add_i32 s1, 0, 0x26000
	v_writelane_b32 v236, s1, 20
	s_add_i32 s1, 0, 0x26028
	v_writelane_b32 v236, s1, 21
	s_add_i32 s1, 0, 0x26020
	v_writelane_b32 v236, s1, 22
	s_add_i32 s1, 0, 0x26060
	v_writelane_b32 v236, s1, 23
	s_add_i32 s1, 0, 0x260c4
	v_writelane_b32 v236, s1, 24
	s_add_i32 s1, 0, 0x26038
	s_and_b32 s0, s0, 0x3c0
	v_writelane_b32 v236, s1, 25
	s_add_i32 s1, 0, 0x21300
	v_writelane_b32 v236, s1, 26
	s_lshl_b32 s0, s0, 1
	v_writelane_b32 v236, s0, 27
	s_add_i32 s81, 0, 0x26030
	s_add_i32 s87, 0, 0x26008
	v_writelane_b32 v236, s1, 28
	s_add_i32 s0, 0, 0x1f800
	v_writelane_b32 v236, s0, 29
	s_add_i32 s0, 0, 0x26058
	v_writelane_b32 v236, s0, 30
	s_add_i32 s0, 0, 0x19a00
	v_writelane_b32 v236, s0, 31
	s_add_i32 s0, 0, 0x15000
	v_writelane_b32 v236, s0, 32
	s_add_i32 s0, 0, 0x11400
	v_writelane_b32 v236, s0, 33
	s_add_i32 s0, 0, 0x19800
	v_writelane_b32 v236, s0, 34
	s_add_i32 s0, 0, 0x26018
	v_writelane_b32 v236, s0, 35
	s_add_i32 s0, 0, 0x26068
	v_writelane_b32 v236, s0, 36
	s_add_i32 s0, 0, 0x26048
	v_writelane_b32 v236, s0, 37
	s_add_i32 s0, 0, 0x26040
	v_writelane_b32 v236, s0, 38
	s_add_i32 s0, 0, 0x26050
	v_writelane_b32 v236, s0, 39
	v_cmp_eq_u32_e64 s[0:1], 0, v0
	s_ashr_i32 s53, s52, 31
	s_add_i32 s94, 0, 0x260c0
	v_writelane_b32 v236, s0, 40
	s_lshl_b64 s[82:83], s[52:53], 12
	s_lshl_b64 s[70:71], s[52:53], 14
	v_writelane_b32 v236, s1, 41
	v_mbcnt_lo_u32_b32 v1, -1, 0
	v_writelane_b32 v236, s0, 42
	s_ashr_i32 s91, s50, 31
	s_lshl_b32 s85, s50, 19
	v_writelane_b32 v236, s1, 43
	v_writelane_b32 v236, s76, 44
	s_lshl_b32 s59, s50, 23
	v_mov_b32_e32 v187, s78
	v_writelane_b32 v236, s77, 45
	v_writelane_b32 v236, s75, 46
	v_writelane_b32 v236, s78, 47
	v_writelane_b32 v236, s79, 48
	v_writelane_b32 v236, s80, 49
	v_writelane_b32 v236, s81, 50
	v_writelane_b32 v236, s87, 51
	v_writelane_b32 v236, s94, 52
	v_writelane_b32 v236, s82, 53
	v_mov_b32_e32 v113, 0
	s_movk_i32 s95, 0x84
	v_writelane_b32 v236, s83, 54
	v_writelane_b32 v236, s70, 55
	s_add_i32 s38, 0, 0x26010
	s_mov_b32 s88, 0xffff0000
	s_mov_b32 s89, 0xffff
	v_mov_b32_e32 v188, 0x358637bd
	s_mov_b32 s92, 0x800000
	s_movk_i32 s93, 0x2000
	v_mov_b32_e32 v189, 1
	s_mov_b32 s56, 0xfe03f81
	s_movk_i32 s57, 0xff7f
	s_mov_b32 s64, 0x3f317217
	s_mov_b32 s65, 0x7f800000
	s_mov_b32 s41, 0x409b43d5
	v_mbcnt_hi_u32_b32 v190, -1, v1
	v_mov_b32_e32 v191, 0x41b17218
	v_mov_b32_e32 v192, 0x7f800000
	s_mov_b32 s84, 0x42e60000
	s_mov_b32 s86, 0x1800000
	s_mov_b32 s68, 0x1801000
	s_mov_b32 s61, 0
	s_lshl_b64 s[62:63], s[52:53], 6
	s_lshl_b64 s[66:67], s[52:53], 11
	s_mov_b64 s[72:73], 0x80
	s_mov_b32 s74, 0x3d800000
	s_mov_b32 s96, 0x41800000
	s_mov_b64 s[98:99], 0x1800
	s_brev_b32 s90, 60
	s_mov_b32 s47, 0x20000
	v_writelane_b32 v236, s71, 56
	v_writelane_b32 v236, s38, 57
	s_branch .LBB0_6

; #define LAS __attribute__((address_space(3)))
; __device__ __forceinline__ void attn_mfma(const GAS bf16* proj, GAS bf16* part, GAS float* lse, int TOKG, const GAS float* qgain, const GAS float* kgain, const GAS float* rel_bias,
;                                           unsigned char* lds, int tid, int lane, int wave, int bid, int G) {
;     ...
;     LAS int* bkt = (LAS int*)(L + ATT_BIAS + 768);
;     for (int e = tid; e < 3 * 129; e += 512) { const int pp = e / 129, dl = e - 129 * pp, dist = dl << (2 * pp); int bk;
;         if (dist < 16) bk = dist; else { const float scl = logf((float)dist / 16.f) / logf(128.f); const int lg = 16 + (int)(scl * 16.f); bk = lg < 31 ? lg : 31; }
;         bkt[e] = bk; }
;     __syncthreads();
;     if (bid < nunits) ATT_ISSUE(bid);
;     for (int u = bid; u < nunits; u += G) {
;         ATT_DEC(u, )
.LBB0_285:
	s_or_b64 exec, exec, s[8:9]
	s_ashr_i32 s0, s34, 31
	s_lshr_b32 s0, s0, 19
	s_add_i32 s0, s34, s0
	s_ashr_i32 s3, s0, 13
	s_mulk_i32 s3, 0x600
	s_cmp_lt_i32 s101, s3
	v_and_b32_e32 v3, 7, v178
	v_ashrrev_i32_e32 v1, 3, v178
	s_cselect_b64 s[0:1], -1, 0
	v_lshrrev_b32_e32 v2, 5, v41
	v_and_b32_e32 v0, 31, v178
	s_and_b64 vcc, exec, s[0:1]
	v_lshlrev_b32_e32 v179, 1, v1
	v_lshlrev_b32_e32 v112, 4, v3
	s_waitcnt lgkmcnt(0)
	s_barrier
	s_cbranch_vccz .LBB0_287
	v_readlane_b32 s4, v236, 8
	v_readlane_b32 s10, v236, 27
	v_mov_b32_e32 v7, v113
	v_add_u32_e32 v3, s4, v179
	s_add_u32 s4, s22, s10
	s_addc_u32 s5, s23, 0
	v_lshl_add_u64 v[4:5], s[4:5], 0, v[112:113]
	v_max_i32_e32 v6, 0, v3
	v_readlane_b32 s5, v236, 6
	v_readlane_b32 s8, v236, 9
	v_readlane_b32 s9, v236, 10
	v_lshlrev_b64 v[6:7], s5, v[6:7]
	v_readlane_b32 s6, v236, 7
	v_lshl_add_u64 v[6:7], v[6:7], 0, s[8:9]
	v_lshlrev_b64 v[6:7], 14, v[6:7]
	v_lshl_add_u64 v[6:7], v[4:5], 0, v[6:7]
	v_add_co_u32_e32 v6, vcc, s93, v6
	s_lshl_b32 s4, s28, 5
	s_nop 0
	v_addc_co_u32_e32 v7, vcc, 0, v7, vcc
	global_load_dwordx4 v[114:117], v[6:7], off
	global_load_dwordx4 v[118:121], v[6:7], off offset:2048
	v_or_b32_e32 v6, 1, v3
	v_max_i32_e32 v6, 0, v6
	v_mov_b32_e32 v7, v113
	v_lshlrev_b64 v[6:7], s5, v[6:7]
	v_lshl_add_u64 v[6:7], v[6:7], 0, s[8:9]
	v_lshlrev_b64 v[6:7], 14, v[6:7]
	v_lshl_add_u64 v[6:7], v[4:5], 0, v[6:7]
	v_add_co_u32_e32 v6, vcc, s93, v6
	s_add_i32 s4, s4, s6
	s_nop 0
	v_addc_co_u32_e32 v7, vcc, 0, v7, vcc
	global_load_dwordx4 v[122:125], v[6:7], off
	global_load_dwordx4 v[126:129], v[6:7], off offset:2048
	v_add_u32_e32 v6, s6, v179
	v_max_i32_e32 v6, 0, v6
	v_mov_b32_e32 v7, v113
	v_lshlrev_b64 v[6:7], s5, v[6:7]
	v_lshl_add_u64 v[6:7], v[6:7], 0, s[8:9]
	v_lshlrev_b64 v[6:7], 14, v[6:7]
	v_lshl_add_u64 v[6:7], v[4:5], 0, v[6:7]
	v_add_co_u32_e32 v6, vcc, s93, v6
	v_readlane_b32 s11, v236, 28
	s_nop 0
	v_addc_co_u32_e32 v7, vcc, 0, v7, vcc
	global_load_dwordx4 v[134:137], v[6:7], off
	global_load_dwordx4 v[130:133], v[6:7], off offset:2048
	v_max_i32_e32 v6, 0xffffff7f, v3
	v_add_u32_e32 v6, 0x81, v6
	v_mov_b32_e32 v7, v113
	v_lshlrev_b64 v[6:7], s5, v[6:7]
	v_lshl_add_u64 v[6:7], v[6:7], 0, s[8:9]
	v_lshlrev_b64 v[6:7], 14, v[6:7]
	v_lshl_add_u64 v[6:7], v[4:5], 0, v[6:7]
	v_add_co_u32_e32 v6, vcc, s93, v6
	s_mov_b32 s11, s61
	s_nop 0
	v_addc_co_u32_e32 v7, vcc, 0, v7, vcc
	global_load_dwordx4 v[142:145], v[6:7], off
	global_load_dwordx4 v[138:141], v[6:7], off offset:2048
	v_max_i32_e32 v6, 0xffffff00, v3
	v_add_u32_e32 v6, 0x100, v6
	v_mov_b32_e32 v7, v113
	v_lshlrev_b64 v[6:7], s5, v[6:7]
	v_lshl_add_u64 v[6:7], v[6:7], 0, s[8:9]
	v_lshlrev_b64 v[6:7], 14, v[6:7]
	v_lshl_add_u64 v[6:7], v[4:5], 0, v[6:7]
	v_add_co_u32_e32 v6, vcc, s93, v6
	v_max_i32_e32 v3, 0xfffffeff, v3
	s_nop 0
	v_addc_co_u32_e32 v7, vcc, 0, v7, vcc
	global_load_dwordx4 v[150:153], v[6:7], off
	global_load_dwordx4 v[146:149], v[6:7], off offset:2048
	v_add_u32_e32 v6, 0x101, v3
	v_mov_b32_e32 v7, v113
	v_lshlrev_b64 v[6:7], s5, v[6:7]
	v_lshl_add_u64 v[6:7], v[6:7], 0, s[8:9]
	v_lshlrev_b64 v[6:7], 14, v[6:7]
	v_lshl_add_u64 v[4:5], v[4:5], 0, v[6:7]
	v_add_co_u32_e32 v4, vcc, s93, v4
	v_lshlrev_b32_e32 v6, 4, v2
	s_nop 0
	v_addc_co_u32_e32 v5, vcc, 0, v5, vcc
	global_load_dwordx4 v[158:161], v[4:5], off
	global_load_dwordx4 v[154:157], v[4:5], off offset:2048
	v_or_b32_e32 v4, s4, v0
	v_ashrrev_i32_e32 v5, 31, v4
	v_lshlrev_b64 v[4:5], s5, v[4:5]
	v_lshl_add_u64 v[4:5], v[4:5], 0, s[8:9]
	v_lshlrev_b64 v[4:5], 14, v[4:5]
	v_lshl_add_u64 v[4:5], s[22:23], 0, v[4:5]
	v_lshl_add_u64 v[4:5], v[4:5], 0, s[10:11]
	v_mov_b32_e32 v7, v113
	v_lshl_add_u64 v[4:5], v[4:5], 0, v[6:7]
	v_lshl_add_u64 v[6:7], v[4:5], 0, s[98:99]
	v_add_co_u32_e32 v4, vcc, 0x1000, v4
	s_mov_b32 s4, s10
	s_nop 0
	v_addc_co_u32_e32 v5, vcc, 0, v5, vcc
	global_load_dwordx4 v[88:91], v[6:7], off offset:32
	global_load_dwordx4 v[84:87], v[6:7], off offset:64
	global_load_dwordx4 v[92:95], v[4:5], off offset:2048
	global_load_dwordx4 v[80:83], v[6:7], off offset:96
	v_writelane_b32 v236, s4, 27
	s_nop 1
	v_writelane_b32 v236, s5, 28
.LBB0_287:
	s_andn2_b64 vcc, exec, s[0:1]
	s_cbranch_vccnz .LBB0_328
	v_lshlrev_b32_e32 v4, 2, v2
	v_readlane_b32 s8, v236, 29
	v_sub_u32_e32 v7, v4, v0
	v_and_b32_e32 v8, 64, v190
	s_mul_i32 s0, s34, 0x1800
	v_lshl_add_u32 v197, v7, 2, s8
	v_xor_b32_e32 v7, 32, v190
	v_add_u32_e32 v8, 64, v8
	s_mul_hi_i32 s1, s34, 0x1800
	s_add_u32 s0, s24, s0
	v_cmp_lt_i32_e32 vcc, v7, v8
	s_addc_u32 s1, s25, s1
	s_lshl_b32 s10, s28, 5
	v_cndmask_b32_e32 v7, v190, v7, vcc
	s_movk_i32 s11, 0x120
	s_cmp_lt_i32 s28, 4
	v_lshlrev_b32_e32 v198, 2, v7
	v_mul_lo_u32 v7, v1, s11
	s_movk_i32 s11, 0x180
	s_cselect_b64 s[26:27], -1, 0
	v_mul_lo_u32 v1, v1, s11
	s_add_i32 s11, s10, 32
	v_lshrrev_b32_e32 v3, 2, v178
	v_and_b32_e32 v5, 16, v178
	v_lshlrev_b32_e32 v6, 2, v41
	v_or_b32_e32 v12, s11, v0
	s_add_i32 s11, s10, 64
	v_and_or_b32 v3, v3, 3, v4
	v_and_or_b32 v5, v6, 12, v5
	s_movk_i32 s12, 0xc0
	v_or_b32_e32 v195, s10, v0
	v_or_b32_e32 v8, 1, v179
	v_or_b32_e32 v13, s11, v0
	s_add_i32 s11, s10, 0x60
	s_addk_i32 s10, 0x80
	v_lshlrev_b32_e32 v5, 1, v5
	v_subrev_u32_e32 v6, 32, v178
	s_movk_i32 s6, 0x81
	s_sub_i32 s35, 4, s28
	v_mad_u32_u24 v3, v3, s12, 0
	s_movk_i32 s13, 0x90
	v_mul_lo_u32 v199, v8, s12
	v_or_b32_e32 v14, s11, v0
	v_or_b32_e32 v0, s10, v0
	s_mulk_i32 s28, 0x1800
	v_cmp_gt_u32_e64 s[6:7], s6, v6
	v_add_u32_e32 v194, 0, v112
	v_lshlrev_b32_e32 v6, 3, v2
	v_lshl_add_u32 v2, v2, 4, 0
	v_mul_lo_u32 v9, v8, s13
	v_add_u32_e32 v8, 0x5f40, v199
	v_add_u32_e32 v10, 0xbf40, v199
	v_mul_lo_u32 v11, v195, s13
	v_mul_lo_u32 v12, v12, s13
	v_mul_lo_u32 v13, v13, s13
	v_mul_lo_u32 v14, v14, s13
	v_mul_lo_u32 v0, v0, s13
	v_add3_u32 v200, v3, v5, s28
	v_cmp_gt_i32_e64 s[4:5], s12, v178
	v_lshl_add_u32 v193, v178, 2, s8
	v_add_u32_e32 v196, 0xffffff80, v179
	v_lshl_add_u64 v[180:181], s[22:23], 0, v[112:113]
	v_cmp_gt_u32_e64 s[8:9], 32, v41
	v_add_u32_e32 v201, 0xd800, v200
	v_add_u32_e32 v202, v194, v7
	v_add_u32_e32 v203, v194, v1
	v_add_u32_e32 v204, v194, v9
	v_add_u32_e32 v205, v194, v8
	v_add_u32_e32 v206, v194, v10
	v_lshlrev_b32_e32 v182, 1, v6
	v_add_u32_e32 v207, v2, v11
	v_add_u32_e32 v208, v2, v12
	v_add_u32_e32 v209, v2, v13
	v_add_u32_e32 v210, v2, v14
	v_add_u32_e32 v211, v2, v0
	v_lshlrev_b32_e32 v112, 1, v4
	s_mov_b32 s14, s101
	s_branch .LBB0_290
